# attention: QK double-buffered reads + PV row sums first with 6 V-fragment buffers (deeper LDS prefetch)
# speedup vs baseline: 1.0112x; 1.0077x over previous
; __device__ __forceinline__ unsigned cvtpk(float lo, float hi) { return pg8::cvt_pk_bf16(lo, hi); }
; __device__ __forceinline__ f32x4 mma16(bf16x8 a, bf16x8 b, f32x4 c) { return __builtin_amdgcn_mfma_f32_16x16x32_bf16(a, b, c, 0, 0, 0); }
; __device__ __forceinline__ void attn_phase(LAS unsigned char* lds, const bf16_t* proj, bf16_t* oa, const float* lamp, const float* subg, const float* relb, const float* qg, int wg, int tid) {
;     ...
;                 bf16x8 pf[2];
; #pragma unroll
;                 for (int s = 0; s < 2; ++s) { float ps = 0.f;
; #pragma unroll
;                     for (int T = 0; T < 2; ++T)
; #pragma unroll
;                         for (int r = 0; r < 4; ++r) { const float p = __builtin_amdgcn_exp2f(st[s][T][r]); st[s][T][r] = p; ps += p; }
;                     if (s == 0) l0 += ps; else l1 += ps;
;                     u32x4 w; w.x = cvtpk(st[s][0][0], st[s][0][1]); w.y = cvtpk(st[s][0][2], st[s][0][3]); w.z = cvtpk(st[s][1][0], st[s][1][1]); w.w = cvtpk(st[s][1][2], st[s][1][3]);
;                     pf[s] = __builtin_bit_cast(bf16x8, w); }
; #pragma unroll
;                 for (int vt = 0; vt < 16; ++vt) { const bf16x8 vf = frag_tr2(Vc, VP, 4 * fq, 16 + 4 * fq, 16 * vt, fr);
;                     o[0][vt] = mma16(vf, pf[0], o[0][vt]); o[1][vt] = mma16(vf, pf[1], o[1][vt]); }
.LBB0_633:
	s_mul_i32 s30, s46, 0x4400
	v_add_u32_e32 v0, s30, v246
	v_exp_f32_e32 v231, v146
	v_exp_f32_e32 v229, v147
	v_exp_f32_e32 v227, v148
	v_exp_f32_e32 v225, v149
	v_exp_f32_e32 v223, v150
	v_exp_f32_e32 v221, v151
	v_exp_f32_e32 v165, v152
	v_exp_f32_e32 v163, v153
	v_exp_f32_e32 v230, v158
	v_exp_f32_e32 v228, v159
	v_exp_f32_e32 v226, v160
	v_exp_f32_e32 v224, v161
	v_exp_f32_e32 v222, v154
	v_exp_f32_e32 v220, v155
	v_exp_f32_e32 v164, v156
	v_exp_f32_e32 v162, v157
	ds_read_b64_tr_b16 v[158:159], v0 offset:36864
	ds_read_b64_tr_b16 v[160:161], v0 offset:45568
	ds_read_b64_tr_b16 v[154:155], v0 offset:36896
	ds_read_b64_tr_b16 v[156:157], v0 offset:45600
	v_cvt_pk_bf16_f32 v146, v231, v229
	v_cvt_pk_bf16_f32 v147, v227, v225
	v_cvt_pk_bf16_f32 v148, v223, v221
	v_cvt_pk_bf16_f32 v149, v165, v163
	v_cvt_pk_bf16_f32 v150, v230, v228
	v_cvt_pk_bf16_f32 v151, v226, v224
	v_cvt_pk_bf16_f32 v152, v222, v220
	v_cvt_pk_bf16_f32 v153, v164, v162
	v_add_f32_e64 v230, v230, 0
	v_add_f32_e64 v231, v231, 0
	v_pk_add_f32 v[228:229], v[228:229], v[230:231]
	v_pk_add_f32 v[226:227], v[226:227], v[228:229]
	v_add_f32_e64 v226, v224, v226
	v_add_f32_e64 v227, v225, v227
	v_pk_add_f32 v[226:227], v[222:223], v[226:227]
	v_add_f32_e64 v226, v220, v226
	v_add_f32_e64 v227, v221, v227
	v_pk_add_f32 v[226:227], v[164:165], v[226:227]
	v_add_f32_e64 v226, v162, v226
	v_add_f32_e64 v227, v163, v227
	v_pk_add_f32 v[218:219], v[218:219], v[226:227]
	ds_read_b64_tr_b16 v[162:163], v0 offset:36928
	ds_read_b64_tr_b16 v[164:165], v0 offset:45632
	ds_read_b64_tr_b16 v[220:221], v0 offset:36960
	ds_read_b64_tr_b16 v[222:223], v0 offset:45664
	ds_read_b64_tr_b16 v[224:225], v0 offset:36992
	ds_read_b64_tr_b16 v[226:227], v0 offset:45696
	ds_read_b64_tr_b16 v[228:229], v0 offset:37024
	ds_read_b64_tr_b16 v[230:231], v0 offset:45728
	s_waitcnt lgkmcnt(10)
	v_mfma_f32_16x16x32_bf16 v[142:145], v[158:161], v[146:149], v[142:145]
	v_mfma_f32_16x16x32_bf16 v[138:141], v[158:161], v[150:153], v[138:141]
	ds_read_b64_tr_b16 v[158:159], v0 offset:37056
	ds_read_b64_tr_b16 v[160:161], v0 offset:45760
	s_waitcnt lgkmcnt(10)
	v_mfma_f32_16x16x32_bf16 v[134:137], v[154:157], v[146:149], v[134:137]
	v_mfma_f32_16x16x32_bf16 v[130:133], v[154:157], v[150:153], v[130:133]
	ds_read_b64_tr_b16 v[154:155], v0 offset:37088
	ds_read_b64_tr_b16 v[156:157], v0 offset:45792
	s_waitcnt lgkmcnt(10)
	v_mfma_f32_16x16x32_bf16 v[126:129], v[162:165], v[146:149], v[126:129]
	v_mfma_f32_16x16x32_bf16 v[122:125], v[162:165], v[150:153], v[122:125]
	ds_read_b64_tr_b16 v[162:163], v0 offset:37120
	ds_read_b64_tr_b16 v[164:165], v0 offset:45824
	s_waitcnt lgkmcnt(10)
	v_mfma_f32_16x16x32_bf16 v[118:121], v[220:223], v[146:149], v[118:121]
	v_mfma_f32_16x16x32_bf16 v[114:117], v[220:223], v[150:153], v[114:117]
	ds_read_b64_tr_b16 v[220:221], v0 offset:37152
	ds_read_b64_tr_b16 v[222:223], v0 offset:45856
	s_waitcnt lgkmcnt(10)
	v_mfma_f32_16x16x32_bf16 v[110:113], v[224:227], v[146:149], v[110:113]
	v_mfma_f32_16x16x32_bf16 v[106:109], v[224:227], v[150:153], v[106:109]
	ds_read_b64_tr_b16 v[224:225], v0 offset:37184
	ds_read_b64_tr_b16 v[226:227], v0 offset:45888
	s_waitcnt lgkmcnt(10)
	v_mfma_f32_16x16x32_bf16 v[102:105], v[228:231], v[146:149], v[102:105]
	v_mfma_f32_16x16x32_bf16 v[98:101], v[228:231], v[150:153], v[98:101]
	ds_read_b64_tr_b16 v[228:229], v0 offset:37216
	ds_read_b64_tr_b16 v[230:231], v0 offset:45920
	s_waitcnt lgkmcnt(10)
	v_mfma_f32_16x16x32_bf16 v[94:97], v[158:161], v[146:149], v[94:97]
	v_mfma_f32_16x16x32_bf16 v[90:93], v[158:161], v[150:153], v[90:93]
	ds_read_b64_tr_b16 v[158:159], v0 offset:37248
	ds_read_b64_tr_b16 v[160:161], v0 offset:45952
	s_waitcnt lgkmcnt(10)
	v_mfma_f32_16x16x32_bf16 v[86:89], v[154:157], v[146:149], v[86:89]
	v_mfma_f32_16x16x32_bf16 v[82:85], v[154:157], v[150:153], v[82:85]
	ds_read_b64_tr_b16 v[154:155], v0 offset:37280
	ds_read_b64_tr_b16 v[156:157], v0 offset:45984
	s_waitcnt lgkmcnt(10)
	v_mfma_f32_16x16x32_bf16 v[78:81], v[162:165], v[146:149], v[78:81]
	v_mfma_f32_16x16x32_bf16 v[74:77], v[162:165], v[150:153], v[74:77]
	ds_read_b64_tr_b16 v[162:163], v0 offset:37312
	ds_read_b64_tr_b16 v[164:165], v0 offset:46016
	s_waitcnt lgkmcnt(10)
	v_mfma_f32_16x16x32_bf16 v[70:73], v[220:223], v[146:149], v[70:73]
	v_mfma_f32_16x16x32_bf16 v[66:69], v[220:223], v[150:153], v[66:69]
	ds_read_b64_tr_b16 v[220:221], v0 offset:37344
	ds_read_b64_tr_b16 v[222:223], v0 offset:46048
	s_waitcnt lgkmcnt(10)
	v_mfma_f32_16x16x32_bf16 v[62:65], v[224:227], v[146:149], v[62:65]
	v_mfma_f32_16x16x32_bf16 v[58:61], v[224:227], v[150:153], v[58:61]
	s_waitcnt lgkmcnt(8)
	v_mfma_f32_16x16x32_bf16 v[54:57], v[228:231], v[146:149], v[54:57]
	v_mfma_f32_16x16x32_bf16 v[50:53], v[228:231], v[150:153], v[50:53]
	s_waitcnt lgkmcnt(6)
	v_mfma_f32_16x16x32_bf16 v[46:49], v[158:161], v[146:149], v[46:49]
	v_mfma_f32_16x16x32_bf16 v[42:45], v[158:161], v[150:153], v[42:45]
	s_waitcnt lgkmcnt(4)
	v_mfma_f32_16x16x32_bf16 v[38:41], v[154:157], v[146:149], v[38:41]
	v_mfma_f32_16x16x32_bf16 v[30:33], v[154:157], v[150:153], v[30:33]
	s_waitcnt lgkmcnt(2)
	v_mfma_f32_16x16x32_bf16 v[34:37], v[162:165], v[146:149], v[34:37]
	v_mfma_f32_16x16x32_bf16 v[22:25], v[162:165], v[150:153], v[22:25]
	s_waitcnt lgkmcnt(0)
	v_mfma_f32_16x16x32_bf16 v[26:29], v[220:223], v[146:149], v[26:29]
	v_mfma_f32_16x16x32_bf16 v[18:21], v[220:223], v[150:153], v[18:21]
	s_andn2_b64 vcc, exec, s[20:21]
	s_cbranch_vccnz .LBB0_594
